# v029 with the attention kv-loop head and the two QK^T-join labels aligned to 64 bytes (phase pin)
# baseline (speedup 1.0000x reference)
.Lprio_skip:
	s_sub_i32 s10, s54, 63
	s_cmp_le_i32 s10, s5
	s_cselect_b64 s[76:77], -1, 0
	s_cmp_gt_i32 s10, s5
	s_cbranch_scc1 .LBB0_396
	ds_read_b128 v[236:239], v196 offset:57344
	ds_read_b128 v[240:243], v207 offset:12288
	ds_read_b128 v[246:249], v197 offset:57344
	ds_read_b128 v[250:253], v205 offset:12288
	ds_read_b128 v[6:9], v195
	ds_read_b128 v[10:13], v195 offset:1024
	ds_read_b128 v[2:5], v195 offset:2048
	v_cvt_pk_bf16_f32 v18, v224, v226
	v_cvt_pk_bf16_f32 v19, v222, v225
	v_cvt_pk_bf16_f32 v20, v220, v223
	v_cvt_pk_bf16_f32 v21, v219, v221
	v_cvt_pk_bf16_f32 v22, v216, v218
	v_cvt_pk_bf16_f32 v23, v214, v217
	v_cvt_pk_bf16_f32 v24, v212, v215
	v_cvt_pk_bf16_f32 v25, v211, v213
	v_add_f32_e32 v0, 0, v224
	v_add_f32_e32 v0, v226, v0
	v_add_f32_e32 v0, v222, v0
	v_add_f32_e32 v0, v225, v0
	v_add_f32_e32 v0, v220, v0
	v_add_f32_e32 v0, v223, v0
	v_add_f32_e32 v0, v219, v0
	v_add_f32_e32 v0, v221, v0
	s_waitcnt lgkmcnt(6)
	v_mfma_f32_32x32x16_bf16 v[112:127], v[236:239], v[156:159], 0
	ds_read_b128 v[236:239], v199 offset:57344
	v_add_f32_e32 v0, v216, v0
	v_add_f32_e32 v0, v218, v0
	v_permlane32_swap_b32_e32 v18, v20
	s_waitcnt lgkmcnt(6)
	v_mfma_f32_32x32x16_bf16 v[96:111], v[240:243], v[156:159], 0
	ds_read_b128 v[240:243], v206 offset:12288
	v_add_f32_e32 v0, v214, v0
	v_add_f32_e32 v0, v217, v0
	v_permlane32_swap_b32_e32 v19, v21
	s_waitcnt lgkmcnt(6)
	v_mfma_f32_32x32x16_bf16 v[112:127], v[246:249], v[152:155], v[112:127]
	ds_read_b128 v[246:249], v198 offset:57344
	v_add_f32_e32 v0, v212, v0
	v_add_f32_e32 v0, v215, v0
	s_waitcnt lgkmcnt(6)
	v_mfma_f32_32x32x16_bf16 v[96:111], v[250:253], v[152:155], v[96:111]
	ds_read_b128 v[250:253], v204 offset:12288
	v_permlane32_swap_b32_e32 v22, v24
	v_add_f32_e32 v0, v211, v0
	s_waitcnt lgkmcnt(3)
	v_mfma_f32_32x32x16_bf16 v[112:127], v[236:239], v[148:151], v[112:127]
	ds_read_b128 v[236:239], v196 offset:57472
	v_add_f32_e32 v0, v213, v0
	v_permlane32_swap_b32_e32 v23, v25
	s_waitcnt lgkmcnt(3)
	v_mfma_f32_32x32x16_bf16 v[96:111], v[240:243], v[148:151], v[96:111]
	ds_read_b128 v[240:243], v207 offset:12416
	v_exp_f32_e32 v182, v182
	v_exp_f32_e32 v183, v183
	s_waitcnt lgkmcnt(3)
	v_mfma_f32_32x32x16_bf16 v[112:127], v[246:249], v[144:147], v[112:127]
	ds_read_b128 v[246:249], v197 offset:57472
	v_exp_f32_e32 v180, v180
	v_exp_f32_e32 v181, v181
	s_waitcnt lgkmcnt(3)
	v_mfma_f32_32x32x16_bf16 v[96:111], v[250:253], v[144:147], v[96:111]
	ds_read_b128 v[250:253], v205 offset:12416
	v_add_f32_e32 v0, v182, v0
	v_exp_f32_e32 v170, v170
	s_waitcnt lgkmcnt(3)
	v_mfma_f32_32x32x16_bf16 v[112:127], v[236:239], v[140:143], v[112:127]
	ds_read_b128 v[236:239], v199 offset:57472
	v_add_f32_e32 v0, v183, v0
	v_exp_f32_e32 v171, v171
	s_waitcnt lgkmcnt(3)
	v_mfma_f32_32x32x16_bf16 v[96:111], v[240:243], v[140:143], v[96:111]
	ds_read_b128 v[240:243], v206 offset:12416
	v_add_f32_e32 v0, v180, v0
	v_exp_f32_e32 v168, v168
	s_waitcnt lgkmcnt(3)
	v_mfma_f32_32x32x16_bf16 v[112:127], v[246:249], v[136:139], v[112:127]
	ds_read_b128 v[246:249], v198 offset:57472
	v_add_f32_e32 v0, v181, v0
	v_exp_f32_e32 v169, v169
	s_waitcnt lgkmcnt(3)
	v_mfma_f32_32x32x16_bf16 v[96:111], v[250:253], v[136:139], v[96:111]
	ds_read_b128 v[250:253], v204 offset:12416
	v_cvt_pk_bf16_f32 v26, v182, v183
	v_cvt_pk_bf16_f32 v27, v180, v181
	s_waitcnt lgkmcnt(3)
	v_mfma_f32_32x32x16_bf16 v[112:127], v[236:239], v[132:135], v[112:127]
	ds_read_b128 v[236:239], v196 offset:57600
	v_add_f32_e32 v0, v170, v0
	v_exp_f32_e32 v166, v166
	s_waitcnt lgkmcnt(3)
	v_mfma_f32_32x32x16_bf16 v[96:111], v[240:243], v[132:135], v[96:111]
	ds_read_b128 v[240:243], v207 offset:12544
	v_add_f32_e32 v0, v171, v0
	v_exp_f32_e32 v167, v167
	s_waitcnt lgkmcnt(3)
	v_mfma_f32_32x32x16_bf16 v[112:127], v[246:249], v[128:131], v[112:127]
	ds_read_b128 v[246:249], v197 offset:57600
	v_add_f32_e32 v0, v168, v0
	v_exp_f32_e32 v164, v164
	s_waitcnt lgkmcnt(3)
	v_mfma_f32_32x32x16_bf16 v[96:111], v[250:253], v[128:131], v[96:111]
	ds_read_b128 v[250:253], v205 offset:12544
	v_add_f32_e32 v0, v169, v0
	v_exp_f32_e32 v165, v165
	s_waitcnt lgkmcnt(3)
	v_mfma_f32_32x32x16_bf16 v[112:127], v[236:239], v[6:9], v[112:127]
	ds_read_b128 v[236:239], v199 offset:57600
	v_cvt_pk_bf16_f32 v28, v170, v171
	v_cvt_pk_bf16_f32 v29, v168, v169
	s_waitcnt lgkmcnt(3)
	v_mfma_f32_32x32x16_bf16 v[96:111], v[240:243], v[6:9], v[96:111]
	ds_read_b128 v[240:243], v206 offset:12544
	ds_read_b128 v[6:9], v195 offset:3072
	v_add_f32_e32 v0, v166, v0
	v_exp_f32_e32 v162, v162
	s_waitcnt lgkmcnt(4)
	v_mfma_f32_32x32x16_bf16 v[112:127], v[246:249], v[10:13], v[112:127]
	ds_read_b128 v[246:249], v198 offset:57600
	v_permlane32_swap_b32_e32 v26, v28
	v_permlane32_swap_b32_e32 v27, v29
	s_waitcnt lgkmcnt(4)
	v_mfma_f32_32x32x16_bf16 v[96:111], v[250:253], v[10:13], v[96:111]
	ds_read_b128 v[250:253], v204 offset:12544
	v_add_f32_e32 v0, v167, v0
	v_exp_f32_e32 v163, v163
	s_waitcnt lgkmcnt(4)
	v_mfma_f32_32x32x16_bf16 v[112:127], v[236:239], v[2:5], v[112:127]
	v_add_f32_e32 v0, v164, v0
	v_exp_f32_e32 v160, v160
	s_waitcnt lgkmcnt(3)
	v_mfma_f32_32x32x16_bf16 v[96:111], v[240:243], v[2:5], v[96:111]
	v_add_f32_e32 v0, v165, v0
	v_exp_f32_e32 v161, v161
	s_waitcnt lgkmcnt(1)
	v_mfma_f32_32x32x16_bf16 v[112:127], v[246:249], v[6:9], v[112:127]
	v_cvt_pk_bf16_f32 v168, v166, v167
	v_cvt_pk_bf16_f32 v169, v164, v165
	s_waitcnt lgkmcnt(0)
	v_mfma_f32_32x32x16_bf16 v[96:111], v[250:253], v[6:9], v[96:111]
	v_add_f32_e32 v0, v162, v0
	v_add_f32_e32 v0, v163, v0
	v_add_f32_e32 v0, v160, v0
	v_add_f32_e32 v0, v161, v0
	v_cvt_pk_bf16_f32 v170, v162, v163
	v_cvt_pk_bf16_f32 v171, v160, v161
	v_mov_b32_e32 v14, v0
	s_nop 1
	v_permlane32_swap_b32_e32 v168, v170
	v_permlane32_swap_b32_e32 v169, v171
	v_permlane32_swap_b32_e32 v0, v14
	s_branch .Lattn_h1_join
	.p2align 6

.LBB0_397:
	v_add_f32_e32 v0, 0, v224
	v_add_f32_e32 v0, v226, v0
	v_add_f32_e32 v0, v222, v0
	v_add_f32_e32 v0, v225, v0
	v_add_f32_e32 v0, v220, v0
	v_add_f32_e32 v0, v223, v0
	v_add_f32_e32 v0, v219, v0
	v_add_f32_e32 v0, v221, v0
	v_add_f32_e32 v0, v216, v0
	v_add_f32_e32 v0, v218, v0
	v_add_f32_e32 v0, v214, v0
	v_add_f32_e32 v0, v217, v0
	v_exp_f32_e32 v2, v182
	v_add_f32_e32 v0, v212, v0
	v_exp_f32_e32 v3, v183
	v_add_f32_e32 v0, v215, v0
	v_exp_f32_e32 v4, v180
	v_add_f32_e32 v0, v211, v0
	v_exp_f32_e32 v5, v181
	v_add_f32_e32 v0, v213, v0
	v_exp_f32_e32 v6, v170
	v_add_f32_e32 v0, v2, v0
	v_exp_f32_e32 v7, v171
	v_add_f32_e32 v0, v3, v0
	v_exp_f32_e32 v8, v168
	v_add_f32_e32 v0, v4, v0
	v_exp_f32_e32 v9, v169
	v_add_f32_e32 v0, v5, v0
	v_exp_f32_e32 v10, v166
	v_add_f32_e32 v0, v6, v0
	v_exp_f32_e32 v11, v167
	v_add_f32_e32 v0, v7, v0
	v_exp_f32_e32 v12, v164
	v_add_f32_e32 v0, v8, v0
	v_exp_f32_e32 v13, v165
	v_add_f32_e32 v0, v9, v0
	v_exp_f32_e32 v15, v162
	v_add_f32_e32 v0, v10, v0
	v_exp_f32_e32 v17, v163
	v_add_f32_e32 v0, v11, v0
	v_exp_f32_e32 v30, v160
	v_add_f32_e32 v0, v12, v0
	v_exp_f32_e32 v31, v161
	v_add_f32_e32 v0, v13, v0
	v_add_f32_e32 v0, v15, v0
	v_add_f32_e32 v0, v17, v0
	v_add_f32_e32 v0, v30, v0
	v_add_f32_e32 v0, v31, v0
	v_mov_b32_e32 v14, v0
	v_cvt_pk_bf16_f32 v18, v224, v226
	v_cvt_pk_bf16_f32 v19, v222, v225
	v_cvt_pk_bf16_f32 v20, v220, v223
	v_cvt_pk_bf16_f32 v21, v219, v221
	v_cvt_pk_bf16_f32 v22, v216, v218
	v_cvt_pk_bf16_f32 v23, v214, v217
	v_cvt_pk_bf16_f32 v24, v212, v215
	v_cvt_pk_bf16_f32 v25, v211, v213
	v_cvt_pk_bf16_f32 v26, v2, v3
	v_cvt_pk_bf16_f32 v27, v4, v5
	v_cvt_pk_bf16_f32 v28, v6, v7
	v_cvt_pk_bf16_f32 v29, v8, v9
	v_cvt_pk_bf16_f32 v168, v10, v11
	v_cvt_pk_bf16_f32 v169, v12, v13
	v_cvt_pk_bf16_f32 v170, v15, v17
	v_cvt_pk_bf16_f32 v171, v30, v31
	s_nop 1
	v_permlane32_swap_b32_e32 v0, v14
	v_permlane32_swap_b32_e32 v18, v20
	v_permlane32_swap_b32_e32 v19, v21
	v_permlane32_swap_b32_e32 v22, v24
	v_permlane32_swap_b32_e32 v23, v25
	v_permlane32_swap_b32_e32 v26, v28
	v_permlane32_swap_b32_e32 v27, v29
	v_permlane32_swap_b32_e32 v168, v170
	v_permlane32_swap_b32_e32 v169, v171
	.p2align 6

.LBB0_408:
	v_add_f32_e32 v17, 0, v216
	v_add_f32_e32 v17, v218, v17
	v_add_f32_e32 v17, v214, v17
	v_add_f32_e32 v17, v217, v17
	v_add_f32_e32 v17, v212, v17
	v_add_f32_e32 v17, v215, v17
	v_add_f32_e32 v17, v211, v17
	v_add_f32_e32 v17, v213, v17
	v_add_f32_e32 v17, v182, v17
	v_add_f32_e32 v17, v208, v17
	v_add_f32_e32 v17, v171, v17
	v_add_f32_e32 v17, v183, v17
	v_exp_f32_e32 v26, v220
	v_add_f32_e32 v17, v169, v17
	v_exp_f32_e32 v27, v221
	v_add_f32_e32 v17, v181, v17
	v_exp_f32_e32 v28, v222
	v_add_f32_e32 v17, v168, v17
	v_exp_f32_e32 v29, v223
	v_add_f32_e32 v17, v170, v17
	v_exp_f32_e32 v31, v224
	v_add_f32_e32 v17, v26, v17
	v_exp_f32_e32 v220, v225
	v_add_f32_e32 v17, v27, v17
	v_exp_f32_e32 v221, v226
	v_add_f32_e32 v17, v28, v17
	v_exp_f32_e32 v222, v227
	v_add_f32_e32 v17, v29, v17
	v_exp_f32_e32 v223, v228
	v_add_f32_e32 v17, v31, v17
	v_exp_f32_e32 v224, v229
	v_add_f32_e32 v17, v220, v17
	v_exp_f32_e32 v225, v230
	v_add_f32_e32 v17, v221, v17
	v_exp_f32_e32 v226, v231
	v_add_f32_e32 v17, v222, v17
	v_exp_f32_e32 v227, v232
	v_add_f32_e32 v17, v223, v17
	v_exp_f32_e32 v228, v233
	v_add_f32_e32 v17, v224, v17
	v_exp_f32_e32 v229, v234
	v_add_f32_e32 v17, v225, v17
	v_exp_f32_e32 v219, v219
	v_add_f32_e32 v17, v226, v17
	v_add_f32_e32 v17, v227, v17
	v_add_f32_e32 v17, v228, v17
	v_add_f32_e32 v17, v229, v17
	v_add_f32_e32 v17, v219, v17
	v_mov_b32_e32 v30, v17
	v_cvt_pk_bf16_f32 v18, v216, v218
	v_cvt_pk_bf16_f32 v19, v214, v217
	v_cvt_pk_bf16_f32 v20, v212, v215
	v_cvt_pk_bf16_f32 v21, v211, v213
	v_cvt_pk_bf16_f32 v22, v182, v208
	v_cvt_pk_bf16_f32 v23, v171, v183
	v_cvt_pk_bf16_f32 v24, v169, v181
	v_cvt_pk_bf16_f32 v25, v168, v170
	v_cvt_pk_bf16_f32 v26, v26, v27
	v_cvt_pk_bf16_f32 v27, v28, v29
	v_cvt_pk_bf16_f32 v28, v31, v220
	v_cvt_pk_bf16_f32 v29, v221, v222
	v_cvt_pk_bf16_f32 v168, v223, v224
	v_cvt_pk_bf16_f32 v169, v225, v226
	v_cvt_pk_bf16_f32 v170, v227, v228
	v_cvt_pk_bf16_f32 v171, v229, v219
	s_nop 1
	v_permlane32_swap_b32_e32 v17, v30
	v_permlane32_swap_b32_e32 v18, v20
	v_permlane32_swap_b32_e32 v19, v21
	v_permlane32_swap_b32_e32 v22, v24
	v_permlane32_swap_b32_e32 v23, v25
	v_permlane32_swap_b32_e32 v26, v28
	v_permlane32_swap_b32_e32 v27, v29
	v_permlane32_swap_b32_e32 v168, v170
	v_permlane32_swap_b32_e32 v169, v171
	.p2align 6
